# P7: rotate workgroup index for K and V up-projection unit deal (balance 12->10 unit-equivalents)
# baseline (speedup 1.0000x reference)
.LBB0_749:
	s_cmpk_lt_i32 s4, 0x310
	s_cselect_b64 s[2:3], -1, 0
	s_cmpk_gt_i32 s4, 0x30f
	v_readfirstlane_b32 s1, v156
	s_cbranch_scc1 .LBB0_769
	s_ashr_i32 s8, s1, 6
	s_ashr_i32 s14, s1, 8
	s_lshl_b32 s28, s8, 10
	s_add_u32 s29, s90, 0x24000000
	v_readlane_b32 s5, v252, 15
	s_addc_u32 s33, s91, 0
	s_add_i32 s5, s5, 0x68
	s_and_b32 s5, s5, 0xff
	s_ashr_i32 s52, s5, 31
	s_lshr_b32 s0, s52, 29
	s_add_i32 s0, s5, s0
	s_ashr_i32 s4, s0, 3
	s_and_b32 s0, s0, -8
	s_sub_i32 s0, s5, s0
	s_cmp_lt_i32 s0, 0
	s_movk_i32 s53, 0x63
	s_cselect_b32 s5, s53, 0x62
	s_mul_i32 s0, s0, s5
	s_add_i32 s0, s0, s4
	s_ashr_i32 s4, s0, 31
	s_lshr_b32 s4, s4, 26
	s_add_i32 s4, s0, s4
	s_ashr_i32 s4, s4, 6
	s_lshl_b32 s6, s4, 3
	s_sub_i32 s5, 0x62, s6
	s_lshl_b32 s4, s4, 6
	s_min_u32 s7, s5, 8
	s_sub_i32 s9, s0, s4
	s_sext_i32_i8 s0, s9
	v_cvt_f32_ubyte0_e32 v1, s7
	v_cvt_f32_i32_e32 v0, s0
	v_rcp_iflag_f32_e32 v2, v1
	s_ashr_i32 s0, s0, 30
	s_or_b32 s0, s0, 1
	v_lshl_add_u32 v136, v172, 10, v168
	v_mul_f32_e32 v2, v0, v2
	v_trunc_f32_e32 v2, v2
	v_fma_f32 v0, -v2, v1, v0
	v_cvt_i32_f32_e32 v2, v2
	v_cmp_ge_f32_e64 s[4:5], |v0|, v1
	s_and_b64 s[4:5], s[4:5], exec
	s_cselect_b32 s0, s0, 0
	v_readfirstlane_b32 s4, v2
	s_add_i32 s0, s4, s0
	s_mul_i32 s4, s0, s7
	s_sub_i32 s4, s9, s4
	s_sext_i32_i8 s4, s4
	s_add_i32 s4, s6, s4
	s_ashr_i32 s5, s4, 31
	s_bfe_i64 s[30:31], s[0:1], 0x80000
	s_lshl_b64 s[6:7], s[4:5], 18
	s_lshl_b64 s[30:31], s[30:31], 18
	s_add_u32 s44, s29, s30
	s_addc_u32 s45, s33, s31
	s_add_i32 s54, s28, 0
	s_add_i32 m0, s54, 0x10000
	v_lshl_add_u32 v132, v174, 10, v170
	global_load_lds_dwordx4 v136, s[44:45]
	s_add_i32 m0, s54, 0x12000
	s_add_u32 s30, s44, 0x20000
	global_load_lds_dwordx4 v132, s[44:45]
	s_addc_u32 s31, s45, 0
	s_add_i32 m0, s54, 0x14000
	v_lshl_add_u32 v138, v171, 10, v168
	global_load_lds_dwordx4 v136, s[30:31]
	s_add_i32 m0, s54, 0x16000
	v_lshl_add_u32 v134, v173, 10, v170
	global_load_lds_dwordx4 v132, s[30:31]
	v_readlane_b32 s30, v252, 20
	v_readlane_b32 s31, v252, 21
	s_add_u32 s42, s30, s6
	s_addc_u32 s43, s31, s7
	s_add_i32 s55, s54, 0x2000
	s_mov_b32 m0, s54
	s_add_u32 s6, s42, 0x20000
	global_load_lds_dwordx4 v138, s[42:43]
	s_mov_b32 m0, s55
	s_addc_u32 s7, s43, 0
	s_add_i32 s56, s54, 0x4000
	global_load_lds_dwordx4 v134, s[42:43]
	s_mov_b32 m0, s56
	s_add_i32 s57, s54, 0x6000
	global_load_lds_dwordx4 v138, s[6:7]
	s_mov_b32 m0, s57
	v_mov_b32_e32 v129, 0
	global_load_lds_dwordx4 v134, s[6:7]
	v_mov_b32_e32 v137, v129
	v_mov_b32_e32 v133, v129
	v_mov_b32_e32 v139, v129
	v_mov_b32_e32 v135, v129
	s_cmp_eq_u32 s14, 1
	s_mov_b32 s5, 0
	v_lshl_add_u64 v[6:7], s[44:45], 0, v[136:137]
	v_lshl_add_u64 v[4:5], s[44:45], 0, v[132:133]
	v_lshl_add_u64 v[2:3], s[42:43], 0, v[138:139]
	v_lshl_add_u64 v[0:1], s[42:43], 0, v[134:135]
	s_cselect_b64 s[6:7], -1, 0
	s_cmp_lg_u32 s14, 1
	s_movk_i32 s58, 0x2000
	s_cbranch_scc1 .LBB0_752
	s_barrier

.LBB0_755:
	s_add_i32 s68, s68, 1
	v_readlane_b32 s36, v252, 2
	s_mul_i32 s0, s68, s62
	s_mul_hi_u32 s1, s68, s36
	s_add_i32 s1, s1, s0
	s_mul_i32 s0, s68, s36
	v_readlane_b32 s31, v252, 15
	s_add_i32 s31, s31, 0x68
	s_and_b32 s31, s31, 0xff
	s_add_u32 s38, s0, s31
	s_addc_u32 s39, s1, s52
	v_cmp_gt_i64_e32 vcc, s[38:39], v[150:151]
	v_cmp_lt_i64_e64 s[0:1], s[38:39], v[148:149]
	v_readlane_b32 s37, v252, 3
	s_cbranch_vccnz .LBB0_757
	s_ashr_i32 s30, s38, 31
	s_lshr_b32 s30, s30, 29
	s_add_i32 s30, s38, s30
	s_ashr_i32 s31, s30, 3
	s_and_b32 s30, s30, -8
	s_sub_i32 s30, s38, s30
	s_cmp_lt_i32 s30, 0
	s_cselect_b32 s34, s53, 0x62
	s_mul_i32 s30, s30, s34
	s_add_i32 s30, s30, s31
	s_ashr_i32 s31, s30, 31
	s_lshr_b32 s31, s31, 26
	s_add_i32 s31, s30, s31
	s_ashr_i32 s34, s31, 6
	s_lshl_b32 s34, s34, 3
	s_sub_i32 s35, 0x62, s34
	s_min_i32 s35, s35, 8
	s_abs_i32 s36, s35
	v_cvt_f32_u32_e32 v0, s36
	s_sub_i32 s38, 0, s36
	s_andn2_b32 s31, s31, 63
	s_sub_i32 s31, s30, s31
	v_rcp_iflag_f32_e32 v0, v0
	s_abs_i32 s30, s31
	s_xor_b32 s37, s31, s35
	s_ashr_i32 s37, s37, 31
	v_mul_f32_e32 v0, 0x4f7ffffe, v0
	v_cvt_u32_f32_e32 v0, v0
	s_nop 0
	v_readfirstlane_b32 s39, v0
	s_mul_i32 s38, s38, s39
	s_mul_hi_u32 s38, s39, s38
	s_add_i32 s39, s39, s38
	s_mul_hi_u32 s38, s30, s39
	s_mul_i32 s39, s38, s36
	s_sub_i32 s30, s30, s39
	s_add_i32 s40, s38, 1
	s_sub_i32 s39, s30, s36
	s_cmp_ge_u32 s30, s36
	s_cselect_b32 s38, s40, s38
	s_cselect_b32 s30, s39, s30
	s_add_i32 s39, s38, 1
	s_cmp_ge_u32 s30, s36
	s_cselect_b32 s30, s39, s38
	s_xor_b32 s30, s30, s37
	s_sub_i32 s30, s30, s37
	s_mul_i32 s35, s30, s35
	s_sub_i32 s31, s31, s35
	s_add_i32 s34, s34, s31

.LBB0_769:
	s_andn2_b64 vcc, exec, s[2:3]
	v_readfirstlane_b32 s1, v156
	s_cbranch_vccnz .LBB0_793
	s_ashr_i32 s4, s1, 6
	s_ashr_i32 s6, s1, 8
	s_lshl_b32 s28, s4, 10
	s_add_u32 s29, s90, 0x24200000
	v_readlane_b32 s3, v252, 15
	s_addc_u32 s33, s91, 0
	s_add_i32 s3, s3, 0x58
	s_and_b32 s3, s3, 0xff
	s_ashr_i32 s52, s3, 31
	s_lshr_b32 s0, s52, 29
	s_add_i32 s0, s3, s0
	s_ashr_i32 s2, s0, 3
	s_and_b32 s0, s0, -8
	s_sub_i32 s0, s3, s0
	s_cmp_lt_i32 s0, 0
	s_movk_i32 s53, 0x63
	s_cselect_b32 s3, s53, 0x62
	s_mul_i32 s0, s0, s3
	s_add_i32 s0, s0, s2
	s_mul_hi_i32 s2, s0, 0x5397829d
	s_lshr_b32 s3, s2, 31
	s_ashr_i32 s2, s2, 8
	s_add_i32 s2, s2, s3
	s_lshl_b32 s3, s2, 3
	s_mulk_i32 s2, 0x310
	s_sub_i32 s2, s0, s2
	s_sext_i32_i16 s0, s2
	s_bfe_u32 s0, s0, 0x3001c
	s_add_i32 s5, s2, s0
	s_sext_i32_i16 s0, s5
	s_and_b32 s5, s5, 0xfff8
	s_sub_i32 s2, s2, s5
	v_lshlrev_b32_e32 v0, 3, v161
	s_sext_i32_i16 s2, s2
	v_and_b32_e32 v0, 0x3ffff0, v0
	s_lshr_b32 s0, s0, 3
	s_add_i32 s38, s3, s2
	v_add_u32_e32 v0, v162, v0
	s_ashr_i32 s39, s38, 31
	s_bfe_i64 s[8:9], s[0:1], 0x100000
	v_lshl_add_u32 v128, v0, 10, v170
	v_lshlrev_b32_e32 v0, 3, v158
	s_lshl_b64 s[2:3], s[38:39], 18
	s_lshl_b64 s[8:9], s[8:9], 18
	v_readlane_b32 s14, v252, 20
	v_and_b32_e32 v0, 0x3ffff0, v0
	v_readlane_b32 s15, v252, 21
	s_add_u32 s42, s14, s8
	v_add_u32_e32 v0, v159, v0
	s_addc_u32 s43, s15, s9
	s_add_i32 s54, s28, 0
	v_lshl_add_u32 v130, v0, 10, v168
	s_add_i32 m0, s54, 0x10000
	v_mov_b32_e32 v133, 0
	global_load_lds_dwordx4 v130, s[42:43]
	s_add_i32 m0, s54, 0x12000
	s_add_u32 s8, s42, 0x20000
	global_load_lds_dwordx4 v128, s[42:43]
	s_addc_u32 s9, s43, 0
	s_add_i32 m0, s54, 0x14000
	v_mov_b32_e32 v131, v133
	global_load_lds_dwordx4 v130, s[8:9]
	s_add_i32 m0, s54, 0x16000
	s_add_u32 s40, s29, s2
	s_addc_u32 s41, s33, s3
	s_add_i32 s55, s54, 0x2000
	global_load_lds_dwordx4 v128, s[8:9]
	s_mov_b32 m0, s54
	s_add_u32 s2, s40, 0x20000
	global_load_lds_dwordx4 v130, s[40:41]
	s_mov_b32 m0, s55
	s_addc_u32 s3, s41, 0
	s_add_i32 s56, s54, 0x4000
	global_load_lds_dwordx4 v128, s[40:41]
	s_mov_b32 m0, s56
	s_add_i32 s57, s54, 0x6000
	global_load_lds_dwordx4 v130, s[2:3]
	s_mov_b32 m0, s57
	v_mov_b32_e32 v129, v133
	global_load_lds_dwordx4 v128, s[2:3]
	s_cmp_eq_u32 s6, 1
	s_mov_b32 s58, 0
	v_lshl_add_u64 v[6:7], s[42:43], 0, v[130:131]
	v_lshl_add_u64 v[4:5], s[42:43], 0, v[128:129]
	v_lshl_add_u64 v[0:1], s[40:41], 0, v[130:131]
	s_cselect_b64 s[2:3], -1, 0
	s_cmp_lg_u32 s6, 1
	v_lshl_add_u64 v[2:3], s[40:41], 0, v[128:129]
	s_cbranch_scc1 .LBB0_772
	s_barrier

.LBB0_775:
	s_add_i32 s58, s58, 1
	v_readlane_b32 s30, v252, 2
	s_mul_i32 s0, s58, s37
	s_mul_hi_u32 s1, s58, s30
	s_add_i32 s1, s1, s0
	s_mul_i32 s0, s58, s30
	v_readlane_b32 s9, v252, 15
	v_readlane_b32 s31, v252, 3
	s_add_i32 s9, s9, 0x58
	s_and_b32 s9, s9, 0xff
	s_add_u32 s30, s0, s9
	s_addc_u32 s31, s1, s52
	v_cmp_gt_i64_e32 vcc, s[30:31], v[140:141]
	v_cmp_lt_i64_e64 s[0:1], s[30:31], v[138:139]
	s_cbranch_vccnz .LBB0_777
	s_ashr_i32 s8, s30, 31
	s_lshr_b32 s8, s8, 29
	s_add_i32 s8, s30, s8
	s_ashr_i32 s9, s8, 3
	s_and_b32 s8, s8, -8
	s_sub_i32 s8, s30, s8
	s_cmp_lt_i32 s8, 0
	s_cselect_b32 s14, s53, 0x62
	s_mul_i32 s8, s8, s14
	s_add_i32 s8, s8, s9
	s_mul_hi_i32 s9, s8, 0x5397829d
	s_lshr_b32 s14, s9, 31
	s_ashr_i32 s9, s9, 8
	s_add_i32 s9, s9, s14
	s_lshl_b32 s14, s9, 3
	s_sub_i32 s15, 8, s14
	s_min_i32 s15, s15, 8
	s_abs_i32 s30, s15
	v_cvt_f32_u32_e32 v0, s30
	s_sub_i32 s34, 0, s30
	s_mulk_i32 s9, 0x310
	s_sub_i32 s9, s8, s9
	v_rcp_iflag_f32_e32 v0, v0
	s_abs_i32 s8, s9
	s_xor_b32 s31, s9, s15
	s_ashr_i32 s31, s31, 31
	v_mul_f32_e32 v0, 0x4f7ffffe, v0
	v_cvt_u32_f32_e32 v0, v0
	s_nop 0
	v_readfirstlane_b32 s35, v0
	s_mul_i32 s34, s34, s35
	s_mul_hi_u32 s34, s35, s34
	s_add_i32 s35, s35, s34
	s_mul_hi_u32 s34, s8, s35
	s_mul_i32 s35, s34, s30
	s_sub_i32 s8, s8, s35
	s_add_i32 s44, s34, 1
	s_sub_i32 s35, s8, s30
	s_cmp_ge_u32 s8, s30
	s_cselect_b32 s34, s44, s34
	s_cselect_b32 s8, s35, s8
	s_add_i32 s35, s34, 1
	s_cmp_ge_u32 s8, s30
	s_cselect_b32 s8, s35, s34
	s_xor_b32 s8, s8, s31
	s_sub_i32 s8, s8, s31
	s_mul_i32 s15, s8, s15
	s_sub_i32 s9, s9, s15
	s_add_i32 s14, s14, s9
